# scan recurrence: LDS operands requested three steps ahead (five rotating register sets) instead of two
# baseline (speedup 1.0000x reference)
.LBB0_619:
	s_and_saveexec_b64 s[0:1], s[8:9]
	s_xor_b64 s[14:15], exec, s[0:1]
	s_cbranch_execz .LBB0_623
	v_and_b32_e32 v87, 1, v101
	v_mad_u32_u24 v0, v87, s75, 0
	v_lshl_add_u32 v84, v98, 2, v0
	v_lshl_add_u32 v85, v99, 7, v0
	v_lshl_add_u32 v86, v87, 14, v162
	v_add_u32_e32 v86, 0x15000, v86
	ds_read_b128 v[176:179], v85 offset:40960
	ds_read_b128 v[180:183], v85 offset:40976
	ds_read_b128 v[2:5], v84 offset:0
	ds_read_b128 v[6:9], v84 offset:8192
	ds_read_b128 v[10:13], v84 offset:16384
	ds_read_b128 v[14:17], v84 offset:24576
	ds_read_b128 v[18:21], v84 offset:32768
	ds_read_b128 v[24:27], v84 offset:256
	ds_read_b128 v[28:31], v84 offset:8448
	ds_read_b128 v[32:35], v84 offset:16640
	ds_read_b128 v[36:39], v84 offset:24832
	ds_read_b128 v[40:43], v84 offset:33024
	ds_read_b128 v[46:49], v84 offset:512
	ds_read_b128 v[50:53], v84 offset:8704
	ds_read_b128 v[54:57], v84 offset:16896
	ds_read_b128 v[58:61], v84 offset:25088
	ds_read_b128 v[62:65], v84 offset:33280
	s_waitcnt lgkmcnt(10)
	v_pk_mul_f32 v[68:69], v[2:3], v[78:79]
	v_pk_mul_f32 v[70:71], v[176:177], v[14:15] op_sel_hi:[0,1]
	v_pk_mul_f32 v[72:73], v[176:177], v[16:17] op_sel_hi:[0,1]
	v_pk_fma_f32 v[68:69], v[4:5], v[80:81], v[68:69]
	v_pk_fma_f32 v[74:75], v[6:7], v[78:79], v[70:71]
	v_pk_fma_f32 v[76:77], v[8:9], v[80:81], v[72:73]
	v_add_f32_e32 v68, v68, v69
	ds_read_b128 v[106:109], v84 offset:768
	ds_read_b128 v[110:113], v84 offset:8960
	v_add_f32_dpp v68, v68, v68 quad_perm:[1,0,3,2] row_mask:0xf bank_mask:0xf bound_ctrl:1
	ds_read_b128 v[114:117], v84 offset:17152
	ds_read_b128 v[118:121], v84 offset:25344
	v_add_f32_dpp v68, v68, v68 quad_perm:[2,3,0,1] row_mask:0xf bank_mask:0xf bound_ctrl:1
	ds_read_b128 v[122:125], v84 offset:33536
	s_nop 0
	v_add_f32_dpp v68, v68, v68 row_half_mirror row_mask:0xf bank_mask:0xf bound_ctrl:1
	s_nop 1
	v_add_f32_dpp v68, v68, v68 row_ror:8 row_mask:0xf bank_mask:0xf bound_ctrl:1
	v_pk_fma_f32 v[78:79], v[10:11], v[68:69], v[74:75] op_sel_hi:[1,0,1] neg_lo:[0,1,0] neg_hi:[0,1,0]
	v_pk_fma_f32 v[80:81], v[12:13], v[68:69], v[76:77] op_sel_hi:[1,0,1] neg_lo:[0,1,0] neg_hi:[0,1,0]
	s_waitcnt lgkmcnt(10)
	v_pk_mul_f32 v[68:69], v[24:25], v[78:79]
	v_pk_mul_f32 v[82:83], v[18:19], v[78:79]
	v_pk_mul_f32 v[70:71], v[176:177], v[36:37] op_sel:[1,0]
	v_pk_fma_f32 v[68:69], v[26:27], v[80:81], v[68:69]
	v_pk_fma_f32 v[82:83], v[20:21], v[80:81], v[82:83]
	v_pk_mul_f32 v[72:73], v[176:177], v[38:39] op_sel:[1,0]
	v_add_f32_e32 v68, v68, v69
	v_add_f32_e32 v82, v82, v83
	v_pk_fma_f32 v[74:75], v[28:29], v[78:79], v[70:71]
	v_add_f32_dpp v68, v68, v68 quad_perm:[1,0,3,2] row_mask:0xf bank_mask:0xf bound_ctrl:1
	v_add_f32_dpp v82, v82, v82 row_ror:8 row_mask:0xf bank_mask:0xf bound_ctrl:1
	v_pk_fma_f32 v[76:77], v[30:31], v[80:81], v[72:73]
	v_add_f32_dpp v68, v68, v68 quad_perm:[2,3,0,1] row_mask:0xf bank_mask:0xf bound_ctrl:1
	ds_read_b128 v[128:131], v84 offset:1024
	ds_read_b128 v[132:135], v84 offset:9216
	v_add_f32_dpp v68, v68, v68 row_half_mirror row_mask:0xf bank_mask:0xf bound_ctrl:1
	ds_read_b128 v[136:139], v84 offset:17408
	ds_read_b128 v[140:143], v84 offset:25600
	v_add_f32_dpp v68, v68, v68 row_ror:8 row_mask:0xf bank_mask:0xf bound_ctrl:1
	ds_read_b128 v[144:147], v84 offset:33792
	v_pk_fma_f32 v[78:79], v[32:33], v[68:69], v[74:75] op_sel_hi:[1,0,1] neg_lo:[0,1,0] neg_hi:[0,1,0]
	v_pk_fma_f32 v[80:81], v[34:35], v[68:69], v[76:77] op_sel_hi:[1,0,1] neg_lo:[0,1,0] neg_hi:[0,1,0]
	s_waitcnt lgkmcnt(10)
	v_pk_mul_f32 v[68:69], v[46:47], v[78:79]
	v_pk_mul_f32 v[88:89], v[40:41], v[78:79]
	v_pk_mul_f32 v[70:71], v[178:179], v[58:59] op_sel_hi:[0,1]
	v_pk_fma_f32 v[68:69], v[48:49], v[80:81], v[68:69]
	v_pk_fma_f32 v[88:89], v[42:43], v[80:81], v[88:89]
	v_pk_mul_f32 v[72:73], v[178:179], v[60:61] op_sel_hi:[0,1]
	v_add_f32_e32 v68, v68, v69
	v_add_f32_e32 v88, v88, v89
	v_pk_fma_f32 v[74:75], v[50:51], v[78:79], v[70:71]
	v_add_f32_dpp v68, v68, v68 quad_perm:[1,0,3,2] row_mask:0xf bank_mask:0xf bound_ctrl:1
	v_add_f32_dpp v88, v88, v88 row_ror:8 row_mask:0xf bank_mask:0xf bound_ctrl:1
	v_pk_fma_f32 v[76:77], v[52:53], v[80:81], v[72:73]
	v_add_f32_dpp v68, v68, v68 quad_perm:[2,3,0,1] row_mask:0xf bank_mask:0xf bound_ctrl:1
	ds_write2st64_b32 v86, v82, v88 offset0:0 offset1:2
	ds_read_b128 v[2:5], v84 offset:1280
	v_add_f32_dpp v68, v68, v68 row_half_mirror row_mask:0xf bank_mask:0xf bound_ctrl:1
	ds_read_b128 v[6:9], v84 offset:9472
	ds_read_b128 v[10:13], v84 offset:17664
	v_add_f32_dpp v68, v68, v68 row_ror:8 row_mask:0xf bank_mask:0xf bound_ctrl:1
	ds_read_b128 v[14:17], v84 offset:25856
	ds_read_b128 v[18:21], v84 offset:34048
	v_pk_fma_f32 v[78:79], v[54:55], v[68:69], v[74:75] op_sel_hi:[1,0,1] neg_lo:[0,1,0] neg_hi:[0,1,0]
	v_pk_fma_f32 v[80:81], v[56:57], v[68:69], v[76:77] op_sel_hi:[1,0,1] neg_lo:[0,1,0] neg_hi:[0,1,0]
	s_waitcnt lgkmcnt(11)
	v_pk_mul_f32 v[68:69], v[106:107], v[78:79]
	v_pk_mul_f32 v[82:83], v[62:63], v[78:79]
	v_pk_mul_f32 v[70:71], v[178:179], v[118:119] op_sel:[1,0]
	v_pk_fma_f32 v[68:69], v[108:109], v[80:81], v[68:69]
	v_pk_fma_f32 v[82:83], v[64:65], v[80:81], v[82:83]
	v_pk_mul_f32 v[72:73], v[178:179], v[120:121] op_sel:[1,0]
	v_add_f32_e32 v68, v68, v69
	v_add_f32_e32 v82, v82, v83
	v_pk_fma_f32 v[74:75], v[110:111], v[78:79], v[70:71]
	v_add_f32_dpp v68, v68, v68 quad_perm:[1,0,3,2] row_mask:0xf bank_mask:0xf bound_ctrl:1
	v_add_f32_dpp v82, v82, v82 row_ror:8 row_mask:0xf bank_mask:0xf bound_ctrl:1
	v_pk_fma_f32 v[76:77], v[112:113], v[80:81], v[72:73]
	v_add_f32_dpp v68, v68, v68 quad_perm:[2,3,0,1] row_mask:0xf bank_mask:0xf bound_ctrl:1
	ds_read_b128 v[24:27], v84 offset:1536
	ds_read_b128 v[28:31], v84 offset:9728
	v_add_f32_dpp v68, v68, v68 row_half_mirror row_mask:0xf bank_mask:0xf bound_ctrl:1
	ds_read_b128 v[32:35], v84 offset:17920
	ds_read_b128 v[36:39], v84 offset:26112
	v_add_f32_dpp v68, v68, v68 row_ror:8 row_mask:0xf bank_mask:0xf bound_ctrl:1
	ds_read_b128 v[40:43], v84 offset:34304
	v_pk_fma_f32 v[78:79], v[114:115], v[68:69], v[74:75] op_sel_hi:[1,0,1] neg_lo:[0,1,0] neg_hi:[0,1,0]
	v_pk_fma_f32 v[80:81], v[116:117], v[68:69], v[76:77] op_sel_hi:[1,0,1] neg_lo:[0,1,0] neg_hi:[0,1,0]
	s_waitcnt lgkmcnt(11)
	v_pk_mul_f32 v[68:69], v[128:129], v[78:79]
	v_pk_mul_f32 v[88:89], v[122:123], v[78:79]
	v_pk_mul_f32 v[70:71], v[180:181], v[140:141] op_sel_hi:[0,1]
	v_pk_fma_f32 v[68:69], v[130:131], v[80:81], v[68:69]
	v_pk_fma_f32 v[88:89], v[124:125], v[80:81], v[88:89]
	v_pk_mul_f32 v[72:73], v[180:181], v[142:143] op_sel_hi:[0,1]
	v_add_f32_e32 v68, v68, v69
	v_add_f32_e32 v88, v88, v89
	v_pk_fma_f32 v[74:75], v[132:133], v[78:79], v[70:71]
	v_add_f32_dpp v68, v68, v68 quad_perm:[1,0,3,2] row_mask:0xf bank_mask:0xf bound_ctrl:1
	v_add_f32_dpp v88, v88, v88 row_ror:8 row_mask:0xf bank_mask:0xf bound_ctrl:1
	v_pk_fma_f32 v[76:77], v[134:135], v[80:81], v[72:73]
	v_add_f32_dpp v68, v68, v68 quad_perm:[2,3,0,1] row_mask:0xf bank_mask:0xf bound_ctrl:1
	ds_write2st64_b32 v86, v82, v88 offset0:4 offset1:6
	ds_read_b128 v[46:49], v84 offset:1792
	v_add_f32_dpp v68, v68, v68 row_half_mirror row_mask:0xf bank_mask:0xf bound_ctrl:1
	ds_read_b128 v[50:53], v84 offset:9984
	ds_read_b128 v[54:57], v84 offset:18176
	v_add_f32_dpp v68, v68, v68 row_ror:8 row_mask:0xf bank_mask:0xf bound_ctrl:1
	ds_read_b128 v[58:61], v84 offset:26368
	ds_read_b128 v[62:65], v84 offset:34560
	v_pk_fma_f32 v[78:79], v[136:137], v[68:69], v[74:75] op_sel_hi:[1,0,1] neg_lo:[0,1,0] neg_hi:[0,1,0]
	v_pk_fma_f32 v[80:81], v[138:139], v[68:69], v[76:77] op_sel_hi:[1,0,1] neg_lo:[0,1,0] neg_hi:[0,1,0]
	s_waitcnt lgkmcnt(11)
	v_pk_mul_f32 v[68:69], v[2:3], v[78:79]
	v_pk_mul_f32 v[82:83], v[144:145], v[78:79]
	v_pk_mul_f32 v[70:71], v[180:181], v[14:15] op_sel:[1,0]
	v_pk_fma_f32 v[68:69], v[4:5], v[80:81], v[68:69]
	v_pk_fma_f32 v[82:83], v[146:147], v[80:81], v[82:83]
	v_pk_mul_f32 v[72:73], v[180:181], v[16:17] op_sel:[1,0]
	v_add_f32_e32 v68, v68, v69
	v_add_f32_e32 v82, v82, v83
	v_pk_fma_f32 v[74:75], v[6:7], v[78:79], v[70:71]
	v_add_f32_dpp v68, v68, v68 quad_perm:[1,0,3,2] row_mask:0xf bank_mask:0xf bound_ctrl:1
	v_add_f32_dpp v82, v82, v82 row_ror:8 row_mask:0xf bank_mask:0xf bound_ctrl:1
	v_pk_fma_f32 v[76:77], v[8:9], v[80:81], v[72:73]
	v_add_f32_dpp v68, v68, v68 quad_perm:[2,3,0,1] row_mask:0xf bank_mask:0xf bound_ctrl:1
	ds_read_b128 v[168:171], v85 offset:40992
	ds_read_b128 v[172:175], v85 offset:41008
	v_add_f32_dpp v68, v68, v68 row_half_mirror row_mask:0xf bank_mask:0xf bound_ctrl:1
	ds_read_b128 v[106:109], v84 offset:2048
	ds_read_b128 v[110:113], v84 offset:10240
	v_add_f32_dpp v68, v68, v68 row_ror:8 row_mask:0xf bank_mask:0xf bound_ctrl:1
	ds_read_b128 v[114:117], v84 offset:18432
	ds_read_b128 v[118:121], v84 offset:26624
	ds_read_b128 v[122:125], v84 offset:34816
	v_pk_fma_f32 v[78:79], v[10:11], v[68:69], v[74:75] op_sel_hi:[1,0,1] neg_lo:[0,1,0] neg_hi:[0,1,0]
	v_pk_fma_f32 v[80:81], v[12:13], v[68:69], v[76:77] op_sel_hi:[1,0,1] neg_lo:[0,1,0] neg_hi:[0,1,0]
	s_waitcnt lgkmcnt(13)
	v_pk_mul_f32 v[68:69], v[24:25], v[78:79]
	v_pk_mul_f32 v[88:89], v[18:19], v[78:79]
	v_pk_mul_f32 v[70:71], v[182:183], v[36:37] op_sel_hi:[0,1]
	v_pk_fma_f32 v[68:69], v[26:27], v[80:81], v[68:69]
	v_pk_fma_f32 v[88:89], v[20:21], v[80:81], v[88:89]
	v_pk_mul_f32 v[72:73], v[182:183], v[38:39] op_sel_hi:[0,1]
	v_add_f32_e32 v68, v68, v69
	v_add_f32_e32 v88, v88, v89
	v_pk_fma_f32 v[74:75], v[28:29], v[78:79], v[70:71]
	v_add_f32_dpp v68, v68, v68 quad_perm:[1,0,3,2] row_mask:0xf bank_mask:0xf bound_ctrl:1
	v_add_f32_dpp v88, v88, v88 row_ror:8 row_mask:0xf bank_mask:0xf bound_ctrl:1
	v_pk_fma_f32 v[76:77], v[30:31], v[80:81], v[72:73]
	v_add_f32_dpp v68, v68, v68 quad_perm:[2,3,0,1] row_mask:0xf bank_mask:0xf bound_ctrl:1
	ds_write2st64_b32 v86, v82, v88 offset0:8 offset1:10
	ds_read_b128 v[128:131], v84 offset:2304
	v_add_f32_dpp v68, v68, v68 row_half_mirror row_mask:0xf bank_mask:0xf bound_ctrl:1
	ds_read_b128 v[132:135], v84 offset:10496
	ds_read_b128 v[136:139], v84 offset:18688
	v_add_f32_dpp v68, v68, v68 row_ror:8 row_mask:0xf bank_mask:0xf bound_ctrl:1
	ds_read_b128 v[140:143], v84 offset:26880
	ds_read_b128 v[144:147], v84 offset:35072
	v_pk_fma_f32 v[78:79], v[32:33], v[68:69], v[74:75] op_sel_hi:[1,0,1] neg_lo:[0,1,0] neg_hi:[0,1,0]
	v_pk_fma_f32 v[80:81], v[34:35], v[68:69], v[76:77] op_sel_hi:[1,0,1] neg_lo:[0,1,0] neg_hi:[0,1,0]
	s_waitcnt lgkmcnt(13)
	v_pk_mul_f32 v[68:69], v[46:47], v[78:79]
	v_pk_mul_f32 v[82:83], v[40:41], v[78:79]
	v_pk_mul_f32 v[70:71], v[182:183], v[58:59] op_sel:[1,0]
	v_pk_fma_f32 v[68:69], v[48:49], v[80:81], v[68:69]
	v_pk_fma_f32 v[82:83], v[42:43], v[80:81], v[82:83]
	v_pk_mul_f32 v[72:73], v[182:183], v[60:61] op_sel:[1,0]
	v_add_f32_e32 v68, v68, v69
	v_add_f32_e32 v82, v82, v83
	v_pk_fma_f32 v[74:75], v[50:51], v[78:79], v[70:71]
	v_add_f32_dpp v68, v68, v68 quad_perm:[1,0,3,2] row_mask:0xf bank_mask:0xf bound_ctrl:1
	v_add_f32_dpp v82, v82, v82 row_ror:8 row_mask:0xf bank_mask:0xf bound_ctrl:1
	v_pk_fma_f32 v[76:77], v[52:53], v[80:81], v[72:73]
	v_add_f32_dpp v68, v68, v68 quad_perm:[2,3,0,1] row_mask:0xf bank_mask:0xf bound_ctrl:1
	ds_read_b128 v[2:5], v84 offset:2560
	ds_read_b128 v[6:9], v84 offset:10752
	v_add_f32_dpp v68, v68, v68 row_half_mirror row_mask:0xf bank_mask:0xf bound_ctrl:1
	ds_read_b128 v[10:13], v84 offset:18944
	ds_read_b128 v[14:17], v84 offset:27136
	v_add_f32_dpp v68, v68, v68 row_ror:8 row_mask:0xf bank_mask:0xf bound_ctrl:1
	ds_read_b128 v[18:21], v84 offset:35328
	v_pk_fma_f32 v[78:79], v[54:55], v[68:69], v[74:75] op_sel_hi:[1,0,1] neg_lo:[0,1,0] neg_hi:[0,1,0]
	v_pk_fma_f32 v[80:81], v[56:57], v[68:69], v[76:77] op_sel_hi:[1,0,1] neg_lo:[0,1,0] neg_hi:[0,1,0]
	s_waitcnt lgkmcnt(11)
	v_pk_mul_f32 v[68:69], v[106:107], v[78:79]
	v_pk_mul_f32 v[88:89], v[62:63], v[78:79]
	v_pk_mul_f32 v[70:71], v[168:169], v[118:119] op_sel_hi:[0,1]
	v_pk_fma_f32 v[68:69], v[108:109], v[80:81], v[68:69]
	v_pk_fma_f32 v[88:89], v[64:65], v[80:81], v[88:89]
	v_pk_mul_f32 v[72:73], v[168:169], v[120:121] op_sel_hi:[0,1]
	v_add_f32_e32 v68, v68, v69
	v_add_f32_e32 v88, v88, v89
	v_pk_fma_f32 v[74:75], v[110:111], v[78:79], v[70:71]
	v_add_f32_dpp v68, v68, v68 quad_perm:[1,0,3,2] row_mask:0xf bank_mask:0xf bound_ctrl:1
	v_add_f32_dpp v88, v88, v88 row_ror:8 row_mask:0xf bank_mask:0xf bound_ctrl:1
	v_pk_fma_f32 v[76:77], v[112:113], v[80:81], v[72:73]
	v_add_f32_dpp v68, v68, v68 quad_perm:[2,3,0,1] row_mask:0xf bank_mask:0xf bound_ctrl:1
	ds_write2st64_b32 v86, v82, v88 offset0:12 offset1:14
	ds_read_b128 v[24:27], v84 offset:2816
	v_add_f32_dpp v68, v68, v68 row_half_mirror row_mask:0xf bank_mask:0xf bound_ctrl:1
	ds_read_b128 v[28:31], v84 offset:11008
	ds_read_b128 v[32:35], v84 offset:19200
	v_add_f32_dpp v68, v68, v68 row_ror:8 row_mask:0xf bank_mask:0xf bound_ctrl:1
	ds_read_b128 v[36:39], v84 offset:27392
	ds_read_b128 v[40:43], v84 offset:35584
	v_pk_fma_f32 v[78:79], v[114:115], v[68:69], v[74:75] op_sel_hi:[1,0,1] neg_lo:[0,1,0] neg_hi:[0,1,0]
	v_pk_fma_f32 v[80:81], v[116:117], v[68:69], v[76:77] op_sel_hi:[1,0,1] neg_lo:[0,1,0] neg_hi:[0,1,0]
	s_waitcnt lgkmcnt(11)
	v_pk_mul_f32 v[68:69], v[128:129], v[78:79]
	v_pk_mul_f32 v[82:83], v[122:123], v[78:79]
	v_pk_mul_f32 v[70:71], v[168:169], v[140:141] op_sel:[1,0]
	v_pk_fma_f32 v[68:69], v[130:131], v[80:81], v[68:69]
	v_pk_fma_f32 v[82:83], v[124:125], v[80:81], v[82:83]
	v_pk_mul_f32 v[72:73], v[168:169], v[142:143] op_sel:[1,0]
	v_add_f32_e32 v68, v68, v69
	v_add_f32_e32 v82, v82, v83
	v_pk_fma_f32 v[74:75], v[132:133], v[78:79], v[70:71]
	v_add_f32_dpp v68, v68, v68 quad_perm:[1,0,3,2] row_mask:0xf bank_mask:0xf bound_ctrl:1
	v_add_f32_dpp v82, v82, v82 row_ror:8 row_mask:0xf bank_mask:0xf bound_ctrl:1
	v_pk_fma_f32 v[76:77], v[134:135], v[80:81], v[72:73]
	v_add_f32_dpp v68, v68, v68 quad_perm:[2,3,0,1] row_mask:0xf bank_mask:0xf bound_ctrl:1
	ds_read_b128 v[46:49], v84 offset:3072
	ds_read_b128 v[50:53], v84 offset:11264
	v_add_f32_dpp v68, v68, v68 row_half_mirror row_mask:0xf bank_mask:0xf bound_ctrl:1
	ds_read_b128 v[54:57], v84 offset:19456
	ds_read_b128 v[58:61], v84 offset:27648
	v_add_f32_dpp v68, v68, v68 row_ror:8 row_mask:0xf bank_mask:0xf bound_ctrl:1
	ds_read_b128 v[62:65], v84 offset:35840
	v_pk_fma_f32 v[78:79], v[136:137], v[68:69], v[74:75] op_sel_hi:[1,0,1] neg_lo:[0,1,0] neg_hi:[0,1,0]
	v_pk_fma_f32 v[80:81], v[138:139], v[68:69], v[76:77] op_sel_hi:[1,0,1] neg_lo:[0,1,0] neg_hi:[0,1,0]
	s_waitcnt lgkmcnt(11)
	v_pk_mul_f32 v[68:69], v[2:3], v[78:79]
	v_pk_mul_f32 v[88:89], v[144:145], v[78:79]
	v_pk_mul_f32 v[70:71], v[170:171], v[14:15] op_sel_hi:[0,1]
	v_pk_fma_f32 v[68:69], v[4:5], v[80:81], v[68:69]
	v_pk_fma_f32 v[88:89], v[146:147], v[80:81], v[88:89]
	v_pk_mul_f32 v[72:73], v[170:171], v[16:17] op_sel_hi:[0,1]
	v_add_f32_e32 v68, v68, v69
	v_add_f32_e32 v88, v88, v89
	v_pk_fma_f32 v[74:75], v[6:7], v[78:79], v[70:71]
	v_add_f32_dpp v68, v68, v68 quad_perm:[1,0,3,2] row_mask:0xf bank_mask:0xf bound_ctrl:1
	v_add_f32_dpp v88, v88, v88 row_ror:8 row_mask:0xf bank_mask:0xf bound_ctrl:1
	v_pk_fma_f32 v[76:77], v[8:9], v[80:81], v[72:73]
	v_add_f32_dpp v68, v68, v68 quad_perm:[2,3,0,1] row_mask:0xf bank_mask:0xf bound_ctrl:1
	ds_write2st64_b32 v86, v82, v88 offset0:16 offset1:18
	ds_read_b128 v[106:109], v84 offset:3328
	v_add_f32_dpp v68, v68, v68 row_half_mirror row_mask:0xf bank_mask:0xf bound_ctrl:1
	ds_read_b128 v[110:113], v84 offset:11520
	ds_read_b128 v[114:117], v84 offset:19712
	v_add_f32_dpp v68, v68, v68 row_ror:8 row_mask:0xf bank_mask:0xf bound_ctrl:1
	ds_read_b128 v[118:121], v84 offset:27904
	ds_read_b128 v[122:125], v84 offset:36096
	v_pk_fma_f32 v[78:79], v[10:11], v[68:69], v[74:75] op_sel_hi:[1,0,1] neg_lo:[0,1,0] neg_hi:[0,1,0]
	v_pk_fma_f32 v[80:81], v[12:13], v[68:69], v[76:77] op_sel_hi:[1,0,1] neg_lo:[0,1,0] neg_hi:[0,1,0]
	s_waitcnt lgkmcnt(11)
	v_pk_mul_f32 v[68:69], v[24:25], v[78:79]
	v_pk_mul_f32 v[82:83], v[18:19], v[78:79]
	v_pk_mul_f32 v[70:71], v[170:171], v[36:37] op_sel:[1,0]
	v_pk_fma_f32 v[68:69], v[26:27], v[80:81], v[68:69]
	v_pk_fma_f32 v[82:83], v[20:21], v[80:81], v[82:83]
	v_pk_mul_f32 v[72:73], v[170:171], v[38:39] op_sel:[1,0]
	v_add_f32_e32 v68, v68, v69
	v_add_f32_e32 v82, v82, v83
	v_pk_fma_f32 v[74:75], v[28:29], v[78:79], v[70:71]
	v_add_f32_dpp v68, v68, v68 quad_perm:[1,0,3,2] row_mask:0xf bank_mask:0xf bound_ctrl:1
	v_add_f32_dpp v82, v82, v82 row_ror:8 row_mask:0xf bank_mask:0xf bound_ctrl:1
	v_pk_fma_f32 v[76:77], v[30:31], v[80:81], v[72:73]
	v_add_f32_dpp v68, v68, v68 quad_perm:[2,3,0,1] row_mask:0xf bank_mask:0xf bound_ctrl:1
	ds_read_b128 v[128:131], v84 offset:3584
	ds_read_b128 v[132:135], v84 offset:11776
	v_add_f32_dpp v68, v68, v68 row_half_mirror row_mask:0xf bank_mask:0xf bound_ctrl:1
	ds_read_b128 v[136:139], v84 offset:19968
	ds_read_b128 v[140:143], v84 offset:28160
	v_add_f32_dpp v68, v68, v68 row_ror:8 row_mask:0xf bank_mask:0xf bound_ctrl:1
	ds_read_b128 v[144:147], v84 offset:36352
	v_pk_fma_f32 v[78:79], v[32:33], v[68:69], v[74:75] op_sel_hi:[1,0,1] neg_lo:[0,1,0] neg_hi:[0,1,0]
	v_pk_fma_f32 v[80:81], v[34:35], v[68:69], v[76:77] op_sel_hi:[1,0,1] neg_lo:[0,1,0] neg_hi:[0,1,0]
	s_waitcnt lgkmcnt(11)
	v_pk_mul_f32 v[68:69], v[46:47], v[78:79]
	v_pk_mul_f32 v[88:89], v[40:41], v[78:79]
	v_pk_mul_f32 v[70:71], v[172:173], v[58:59] op_sel_hi:[0,1]
	v_pk_fma_f32 v[68:69], v[48:49], v[80:81], v[68:69]
	v_pk_fma_f32 v[88:89], v[42:43], v[80:81], v[88:89]
	v_pk_mul_f32 v[72:73], v[172:173], v[60:61] op_sel_hi:[0,1]
	v_add_f32_e32 v68, v68, v69
	v_add_f32_e32 v88, v88, v89
	v_pk_fma_f32 v[74:75], v[50:51], v[78:79], v[70:71]
	v_add_f32_dpp v68, v68, v68 quad_perm:[1,0,3,2] row_mask:0xf bank_mask:0xf bound_ctrl:1
	v_add_f32_dpp v88, v88, v88 row_ror:8 row_mask:0xf bank_mask:0xf bound_ctrl:1
	v_pk_fma_f32 v[76:77], v[52:53], v[80:81], v[72:73]
	v_add_f32_dpp v68, v68, v68 quad_perm:[2,3,0,1] row_mask:0xf bank_mask:0xf bound_ctrl:1
	ds_write2st64_b32 v86, v82, v88 offset0:20 offset1:22
	ds_read_b128 v[2:5], v84 offset:3840
	v_add_f32_dpp v68, v68, v68 row_half_mirror row_mask:0xf bank_mask:0xf bound_ctrl:1
	ds_read_b128 v[6:9], v84 offset:12032
	ds_read_b128 v[10:13], v84 offset:20224
	v_add_f32_dpp v68, v68, v68 row_ror:8 row_mask:0xf bank_mask:0xf bound_ctrl:1
	ds_read_b128 v[14:17], v84 offset:28416
	ds_read_b128 v[18:21], v84 offset:36608
	v_pk_fma_f32 v[78:79], v[54:55], v[68:69], v[74:75] op_sel_hi:[1,0,1] neg_lo:[0,1,0] neg_hi:[0,1,0]
	v_pk_fma_f32 v[80:81], v[56:57], v[68:69], v[76:77] op_sel_hi:[1,0,1] neg_lo:[0,1,0] neg_hi:[0,1,0]
	s_waitcnt lgkmcnt(11)
	v_pk_mul_f32 v[68:69], v[106:107], v[78:79]
	v_pk_mul_f32 v[82:83], v[62:63], v[78:79]
	v_pk_mul_f32 v[70:71], v[172:173], v[118:119] op_sel:[1,0]
	v_pk_fma_f32 v[68:69], v[108:109], v[80:81], v[68:69]
	v_pk_fma_f32 v[82:83], v[64:65], v[80:81], v[82:83]
	v_pk_mul_f32 v[72:73], v[172:173], v[120:121] op_sel:[1,0]
	v_add_f32_e32 v68, v68, v69
	v_add_f32_e32 v82, v82, v83
	v_pk_fma_f32 v[74:75], v[110:111], v[78:79], v[70:71]
	v_add_f32_dpp v68, v68, v68 quad_perm:[1,0,3,2] row_mask:0xf bank_mask:0xf bound_ctrl:1
	v_add_f32_dpp v82, v82, v82 row_ror:8 row_mask:0xf bank_mask:0xf bound_ctrl:1
	v_pk_fma_f32 v[76:77], v[112:113], v[80:81], v[72:73]
	v_add_f32_dpp v68, v68, v68 quad_perm:[2,3,0,1] row_mask:0xf bank_mask:0xf bound_ctrl:1
	ds_read_b128 v[176:179], v85 offset:41024
	ds_read_b128 v[180:183], v85 offset:41040
	v_add_f32_dpp v68, v68, v68 row_half_mirror row_mask:0xf bank_mask:0xf bound_ctrl:1
	ds_read_b128 v[24:27], v84 offset:4096
	ds_read_b128 v[28:31], v84 offset:12288
	v_add_f32_dpp v68, v68, v68 row_ror:8 row_mask:0xf bank_mask:0xf bound_ctrl:1
	ds_read_b128 v[32:35], v84 offset:20480
	ds_read_b128 v[36:39], v84 offset:28672
	ds_read_b128 v[40:43], v84 offset:36864
	v_pk_fma_f32 v[78:79], v[114:115], v[68:69], v[74:75] op_sel_hi:[1,0,1] neg_lo:[0,1,0] neg_hi:[0,1,0]
	v_pk_fma_f32 v[80:81], v[116:117], v[68:69], v[76:77] op_sel_hi:[1,0,1] neg_lo:[0,1,0] neg_hi:[0,1,0]
	s_waitcnt lgkmcnt(13)
	v_pk_mul_f32 v[68:69], v[128:129], v[78:79]
	v_pk_mul_f32 v[88:89], v[122:123], v[78:79]
	v_pk_mul_f32 v[70:71], v[174:175], v[140:141] op_sel_hi:[0,1]
	v_pk_fma_f32 v[68:69], v[130:131], v[80:81], v[68:69]
	v_pk_fma_f32 v[88:89], v[124:125], v[80:81], v[88:89]
	v_pk_mul_f32 v[72:73], v[174:175], v[142:143] op_sel_hi:[0,1]
	v_add_f32_e32 v68, v68, v69
	v_add_f32_e32 v88, v88, v89
	v_pk_fma_f32 v[74:75], v[132:133], v[78:79], v[70:71]
	v_add_f32_dpp v68, v68, v68 quad_perm:[1,0,3,2] row_mask:0xf bank_mask:0xf bound_ctrl:1
	v_add_f32_dpp v88, v88, v88 row_ror:8 row_mask:0xf bank_mask:0xf bound_ctrl:1
	v_pk_fma_f32 v[76:77], v[134:135], v[80:81], v[72:73]
	v_add_f32_dpp v68, v68, v68 quad_perm:[2,3,0,1] row_mask:0xf bank_mask:0xf bound_ctrl:1
	ds_write2st64_b32 v86, v82, v88 offset0:24 offset1:26
	ds_read_b128 v[46:49], v84 offset:4352
	v_add_f32_dpp v68, v68, v68 row_half_mirror row_mask:0xf bank_mask:0xf bound_ctrl:1
	ds_read_b128 v[50:53], v84 offset:12544
	ds_read_b128 v[54:57], v84 offset:20736
	v_add_f32_dpp v68, v68, v68 row_ror:8 row_mask:0xf bank_mask:0xf bound_ctrl:1
	ds_read_b128 v[58:61], v84 offset:28928
	ds_read_b128 v[62:65], v84 offset:37120
	v_pk_fma_f32 v[78:79], v[136:137], v[68:69], v[74:75] op_sel_hi:[1,0,1] neg_lo:[0,1,0] neg_hi:[0,1,0]
	v_pk_fma_f32 v[80:81], v[138:139], v[68:69], v[76:77] op_sel_hi:[1,0,1] neg_lo:[0,1,0] neg_hi:[0,1,0]
	s_waitcnt lgkmcnt(13)
	v_pk_mul_f32 v[68:69], v[2:3], v[78:79]
	v_pk_mul_f32 v[82:83], v[144:145], v[78:79]
	v_pk_mul_f32 v[70:71], v[174:175], v[14:15] op_sel:[1,0]
	v_pk_fma_f32 v[68:69], v[4:5], v[80:81], v[68:69]
	v_pk_fma_f32 v[82:83], v[146:147], v[80:81], v[82:83]
	v_pk_mul_f32 v[72:73], v[174:175], v[16:17] op_sel:[1,0]
	v_add_f32_e32 v68, v68, v69
	v_add_f32_e32 v82, v82, v83
	v_pk_fma_f32 v[74:75], v[6:7], v[78:79], v[70:71]
	v_add_f32_dpp v68, v68, v68 quad_perm:[1,0,3,2] row_mask:0xf bank_mask:0xf bound_ctrl:1
	v_add_f32_dpp v82, v82, v82 row_ror:8 row_mask:0xf bank_mask:0xf bound_ctrl:1
	v_pk_fma_f32 v[76:77], v[8:9], v[80:81], v[72:73]
	v_add_f32_dpp v68, v68, v68 quad_perm:[2,3,0,1] row_mask:0xf bank_mask:0xf bound_ctrl:1
	ds_read_b128 v[106:109], v84 offset:4608
	ds_read_b128 v[110:113], v84 offset:12800
	v_add_f32_dpp v68, v68, v68 row_half_mirror row_mask:0xf bank_mask:0xf bound_ctrl:1
	ds_read_b128 v[114:117], v84 offset:20992
	ds_read_b128 v[118:121], v84 offset:29184
	v_add_f32_dpp v68, v68, v68 row_ror:8 row_mask:0xf bank_mask:0xf bound_ctrl:1
	ds_read_b128 v[122:125], v84 offset:37376
	v_pk_fma_f32 v[78:79], v[10:11], v[68:69], v[74:75] op_sel_hi:[1,0,1] neg_lo:[0,1,0] neg_hi:[0,1,0]
	v_pk_fma_f32 v[80:81], v[12:13], v[68:69], v[76:77] op_sel_hi:[1,0,1] neg_lo:[0,1,0] neg_hi:[0,1,0]
	s_waitcnt lgkmcnt(11)
	v_pk_mul_f32 v[68:69], v[24:25], v[78:79]
	v_pk_mul_f32 v[88:89], v[18:19], v[78:79]
	v_pk_mul_f32 v[70:71], v[176:177], v[36:37] op_sel_hi:[0,1]
	v_pk_fma_f32 v[68:69], v[26:27], v[80:81], v[68:69]
	v_pk_fma_f32 v[88:89], v[20:21], v[80:81], v[88:89]
	v_pk_mul_f32 v[72:73], v[176:177], v[38:39] op_sel_hi:[0,1]
	v_add_f32_e32 v68, v68, v69
	v_add_f32_e32 v88, v88, v89
	v_pk_fma_f32 v[74:75], v[28:29], v[78:79], v[70:71]
	v_add_f32_dpp v68, v68, v68 quad_perm:[1,0,3,2] row_mask:0xf bank_mask:0xf bound_ctrl:1
	v_add_f32_dpp v88, v88, v88 row_ror:8 row_mask:0xf bank_mask:0xf bound_ctrl:1
	v_pk_fma_f32 v[76:77], v[30:31], v[80:81], v[72:73]
	v_add_f32_dpp v68, v68, v68 quad_perm:[2,3,0,1] row_mask:0xf bank_mask:0xf bound_ctrl:1
	ds_write2st64_b32 v86, v82, v88 offset0:28 offset1:30
	ds_read_b128 v[128:131], v84 offset:4864
	v_add_f32_dpp v68, v68, v68 row_half_mirror row_mask:0xf bank_mask:0xf bound_ctrl:1
	ds_read_b128 v[132:135], v84 offset:13056
	ds_read_b128 v[136:139], v84 offset:21248
	v_add_f32_dpp v68, v68, v68 row_ror:8 row_mask:0xf bank_mask:0xf bound_ctrl:1
	ds_read_b128 v[140:143], v84 offset:29440
	ds_read_b128 v[144:147], v84 offset:37632
	v_pk_fma_f32 v[78:79], v[32:33], v[68:69], v[74:75] op_sel_hi:[1,0,1] neg_lo:[0,1,0] neg_hi:[0,1,0]
	v_pk_fma_f32 v[80:81], v[34:35], v[68:69], v[76:77] op_sel_hi:[1,0,1] neg_lo:[0,1,0] neg_hi:[0,1,0]
	s_waitcnt lgkmcnt(11)
	v_pk_mul_f32 v[68:69], v[46:47], v[78:79]
	v_pk_mul_f32 v[82:83], v[40:41], v[78:79]
	v_pk_mul_f32 v[70:71], v[176:177], v[58:59] op_sel:[1,0]
	v_pk_fma_f32 v[68:69], v[48:49], v[80:81], v[68:69]
	v_pk_fma_f32 v[82:83], v[42:43], v[80:81], v[82:83]
	v_pk_mul_f32 v[72:73], v[176:177], v[60:61] op_sel:[1,0]
	v_add_f32_e32 v68, v68, v69
	v_add_f32_e32 v82, v82, v83
	v_pk_fma_f32 v[74:75], v[50:51], v[78:79], v[70:71]
	v_add_f32_dpp v68, v68, v68 quad_perm:[1,0,3,2] row_mask:0xf bank_mask:0xf bound_ctrl:1
	v_add_f32_dpp v82, v82, v82 row_ror:8 row_mask:0xf bank_mask:0xf bound_ctrl:1
	v_pk_fma_f32 v[76:77], v[52:53], v[80:81], v[72:73]
	v_add_f32_dpp v68, v68, v68 quad_perm:[2,3,0,1] row_mask:0xf bank_mask:0xf bound_ctrl:1
	ds_read_b128 v[2:5], v84 offset:5120
	ds_read_b128 v[6:9], v84 offset:13312
	v_add_f32_dpp v68, v68, v68 row_half_mirror row_mask:0xf bank_mask:0xf bound_ctrl:1
	ds_read_b128 v[10:13], v84 offset:21504
	ds_read_b128 v[14:17], v84 offset:29696
	v_add_f32_dpp v68, v68, v68 row_ror:8 row_mask:0xf bank_mask:0xf bound_ctrl:1
	ds_read_b128 v[18:21], v84 offset:37888
	v_pk_fma_f32 v[78:79], v[54:55], v[68:69], v[74:75] op_sel_hi:[1,0,1] neg_lo:[0,1,0] neg_hi:[0,1,0]
	v_pk_fma_f32 v[80:81], v[56:57], v[68:69], v[76:77] op_sel_hi:[1,0,1] neg_lo:[0,1,0] neg_hi:[0,1,0]
	s_waitcnt lgkmcnt(11)
	v_pk_mul_f32 v[68:69], v[106:107], v[78:79]
	v_pk_mul_f32 v[88:89], v[62:63], v[78:79]
	v_pk_mul_f32 v[70:71], v[178:179], v[118:119] op_sel_hi:[0,1]
	v_pk_fma_f32 v[68:69], v[108:109], v[80:81], v[68:69]
	v_pk_fma_f32 v[88:89], v[64:65], v[80:81], v[88:89]
	v_pk_mul_f32 v[72:73], v[178:179], v[120:121] op_sel_hi:[0,1]
	v_add_f32_e32 v68, v68, v69
	v_add_f32_e32 v88, v88, v89
	v_pk_fma_f32 v[74:75], v[110:111], v[78:79], v[70:71]
	v_add_f32_dpp v68, v68, v68 quad_perm:[1,0,3,2] row_mask:0xf bank_mask:0xf bound_ctrl:1
	v_add_f32_dpp v88, v88, v88 row_ror:8 row_mask:0xf bank_mask:0xf bound_ctrl:1
	v_pk_fma_f32 v[76:77], v[112:113], v[80:81], v[72:73]
	v_add_f32_dpp v68, v68, v68 quad_perm:[2,3,0,1] row_mask:0xf bank_mask:0xf bound_ctrl:1
	ds_write2st64_b32 v86, v82, v88 offset0:32 offset1:34
	ds_read_b128 v[24:27], v84 offset:5376
	v_add_f32_dpp v68, v68, v68 row_half_mirror row_mask:0xf bank_mask:0xf bound_ctrl:1
	ds_read_b128 v[28:31], v84 offset:13568
	ds_read_b128 v[32:35], v84 offset:21760
	v_add_f32_dpp v68, v68, v68 row_ror:8 row_mask:0xf bank_mask:0xf bound_ctrl:1
	ds_read_b128 v[36:39], v84 offset:29952
	ds_read_b128 v[40:43], v84 offset:38144
	v_pk_fma_f32 v[78:79], v[114:115], v[68:69], v[74:75] op_sel_hi:[1,0,1] neg_lo:[0,1,0] neg_hi:[0,1,0]
	v_pk_fma_f32 v[80:81], v[116:117], v[68:69], v[76:77] op_sel_hi:[1,0,1] neg_lo:[0,1,0] neg_hi:[0,1,0]
	s_waitcnt lgkmcnt(11)
	v_pk_mul_f32 v[68:69], v[128:129], v[78:79]
	v_pk_mul_f32 v[82:83], v[122:123], v[78:79]
	v_pk_mul_f32 v[70:71], v[178:179], v[140:141] op_sel:[1,0]
	v_pk_fma_f32 v[68:69], v[130:131], v[80:81], v[68:69]
	v_pk_fma_f32 v[82:83], v[124:125], v[80:81], v[82:83]
	v_pk_mul_f32 v[72:73], v[178:179], v[142:143] op_sel:[1,0]
	v_add_f32_e32 v68, v68, v69
	v_add_f32_e32 v82, v82, v83
	v_pk_fma_f32 v[74:75], v[132:133], v[78:79], v[70:71]
	v_add_f32_dpp v68, v68, v68 quad_perm:[1,0,3,2] row_mask:0xf bank_mask:0xf bound_ctrl:1
	v_add_f32_dpp v82, v82, v82 row_ror:8 row_mask:0xf bank_mask:0xf bound_ctrl:1
	v_pk_fma_f32 v[76:77], v[134:135], v[80:81], v[72:73]
	v_add_f32_dpp v68, v68, v68 quad_perm:[2,3,0,1] row_mask:0xf bank_mask:0xf bound_ctrl:1
	ds_read_b128 v[46:49], v84 offset:5632
	ds_read_b128 v[50:53], v84 offset:13824
	v_add_f32_dpp v68, v68, v68 row_half_mirror row_mask:0xf bank_mask:0xf bound_ctrl:1
	ds_read_b128 v[54:57], v84 offset:22016
	ds_read_b128 v[58:61], v84 offset:30208
	v_add_f32_dpp v68, v68, v68 row_ror:8 row_mask:0xf bank_mask:0xf bound_ctrl:1
	ds_read_b128 v[62:65], v84 offset:38400
	v_pk_fma_f32 v[78:79], v[136:137], v[68:69], v[74:75] op_sel_hi:[1,0,1] neg_lo:[0,1,0] neg_hi:[0,1,0]
	v_pk_fma_f32 v[80:81], v[138:139], v[68:69], v[76:77] op_sel_hi:[1,0,1] neg_lo:[0,1,0] neg_hi:[0,1,0]
	s_waitcnt lgkmcnt(11)
	v_pk_mul_f32 v[68:69], v[2:3], v[78:79]
	v_pk_mul_f32 v[88:89], v[144:145], v[78:79]
	v_pk_mul_f32 v[70:71], v[180:181], v[14:15] op_sel_hi:[0,1]
	v_pk_fma_f32 v[68:69], v[4:5], v[80:81], v[68:69]
	v_pk_fma_f32 v[88:89], v[146:147], v[80:81], v[88:89]
	v_pk_mul_f32 v[72:73], v[180:181], v[16:17] op_sel_hi:[0,1]
	v_add_f32_e32 v68, v68, v69
	v_add_f32_e32 v88, v88, v89
	v_pk_fma_f32 v[74:75], v[6:7], v[78:79], v[70:71]
	v_add_f32_dpp v68, v68, v68 quad_perm:[1,0,3,2] row_mask:0xf bank_mask:0xf bound_ctrl:1
	v_add_f32_dpp v88, v88, v88 row_ror:8 row_mask:0xf bank_mask:0xf bound_ctrl:1
	v_pk_fma_f32 v[76:77], v[8:9], v[80:81], v[72:73]
	v_add_f32_dpp v68, v68, v68 quad_perm:[2,3,0,1] row_mask:0xf bank_mask:0xf bound_ctrl:1
	ds_write2st64_b32 v86, v82, v88 offset0:36 offset1:38
	ds_read_b128 v[106:109], v84 offset:5888
	v_add_f32_dpp v68, v68, v68 row_half_mirror row_mask:0xf bank_mask:0xf bound_ctrl:1
	ds_read_b128 v[110:113], v84 offset:14080
	ds_read_b128 v[114:117], v84 offset:22272
	v_add_f32_dpp v68, v68, v68 row_ror:8 row_mask:0xf bank_mask:0xf bound_ctrl:1
	ds_read_b128 v[118:121], v84 offset:30464
	ds_read_b128 v[122:125], v84 offset:38656
	v_pk_fma_f32 v[78:79], v[10:11], v[68:69], v[74:75] op_sel_hi:[1,0,1] neg_lo:[0,1,0] neg_hi:[0,1,0]
	v_pk_fma_f32 v[80:81], v[12:13], v[68:69], v[76:77] op_sel_hi:[1,0,1] neg_lo:[0,1,0] neg_hi:[0,1,0]
	s_waitcnt lgkmcnt(11)
	v_pk_mul_f32 v[68:69], v[24:25], v[78:79]
	v_pk_mul_f32 v[82:83], v[18:19], v[78:79]
	v_pk_mul_f32 v[70:71], v[180:181], v[36:37] op_sel:[1,0]
	v_pk_fma_f32 v[68:69], v[26:27], v[80:81], v[68:69]
	v_pk_fma_f32 v[82:83], v[20:21], v[80:81], v[82:83]
	v_pk_mul_f32 v[72:73], v[180:181], v[38:39] op_sel:[1,0]
	v_add_f32_e32 v68, v68, v69
	v_add_f32_e32 v82, v82, v83
	v_pk_fma_f32 v[74:75], v[28:29], v[78:79], v[70:71]
	v_add_f32_dpp v68, v68, v68 quad_perm:[1,0,3,2] row_mask:0xf bank_mask:0xf bound_ctrl:1
	v_add_f32_dpp v82, v82, v82 row_ror:8 row_mask:0xf bank_mask:0xf bound_ctrl:1
	v_pk_fma_f32 v[76:77], v[30:31], v[80:81], v[72:73]
	v_add_f32_dpp v68, v68, v68 quad_perm:[2,3,0,1] row_mask:0xf bank_mask:0xf bound_ctrl:1
	ds_read_b128 v[168:171], v85 offset:41056
	ds_read_b128 v[172:175], v85 offset:41072
	v_add_f32_dpp v68, v68, v68 row_half_mirror row_mask:0xf bank_mask:0xf bound_ctrl:1
	ds_read_b128 v[128:131], v84 offset:6144
	ds_read_b128 v[132:135], v84 offset:14336
	v_add_f32_dpp v68, v68, v68 row_ror:8 row_mask:0xf bank_mask:0xf bound_ctrl:1
	ds_read_b128 v[136:139], v84 offset:22528
	ds_read_b128 v[140:143], v84 offset:30720
	ds_read_b128 v[144:147], v84 offset:38912
	v_pk_fma_f32 v[78:79], v[32:33], v[68:69], v[74:75] op_sel_hi:[1,0,1] neg_lo:[0,1,0] neg_hi:[0,1,0]
	v_pk_fma_f32 v[80:81], v[34:35], v[68:69], v[76:77] op_sel_hi:[1,0,1] neg_lo:[0,1,0] neg_hi:[0,1,0]
	s_waitcnt lgkmcnt(13)
	v_pk_mul_f32 v[68:69], v[46:47], v[78:79]
	v_pk_mul_f32 v[88:89], v[40:41], v[78:79]
	v_pk_mul_f32 v[70:71], v[182:183], v[58:59] op_sel_hi:[0,1]
	v_pk_fma_f32 v[68:69], v[48:49], v[80:81], v[68:69]
	v_pk_fma_f32 v[88:89], v[42:43], v[80:81], v[88:89]
	v_pk_mul_f32 v[72:73], v[182:183], v[60:61] op_sel_hi:[0,1]
	v_add_f32_e32 v68, v68, v69
	v_add_f32_e32 v88, v88, v89
	v_pk_fma_f32 v[74:75], v[50:51], v[78:79], v[70:71]
	v_add_f32_dpp v68, v68, v68 quad_perm:[1,0,3,2] row_mask:0xf bank_mask:0xf bound_ctrl:1
	v_add_f32_dpp v88, v88, v88 row_ror:8 row_mask:0xf bank_mask:0xf bound_ctrl:1
	v_pk_fma_f32 v[76:77], v[52:53], v[80:81], v[72:73]
	v_add_f32_dpp v68, v68, v68 quad_perm:[2,3,0,1] row_mask:0xf bank_mask:0xf bound_ctrl:1
	ds_write2st64_b32 v86, v82, v88 offset0:40 offset1:42
	ds_read_b128 v[2:5], v84 offset:6400
	v_add_f32_dpp v68, v68, v68 row_half_mirror row_mask:0xf bank_mask:0xf bound_ctrl:1
	ds_read_b128 v[6:9], v84 offset:14592
	ds_read_b128 v[10:13], v84 offset:22784
	v_add_f32_dpp v68, v68, v68 row_ror:8 row_mask:0xf bank_mask:0xf bound_ctrl:1
	ds_read_b128 v[14:17], v84 offset:30976
	ds_read_b128 v[18:21], v84 offset:39168
	v_pk_fma_f32 v[78:79], v[54:55], v[68:69], v[74:75] op_sel_hi:[1,0,1] neg_lo:[0,1,0] neg_hi:[0,1,0]
	v_pk_fma_f32 v[80:81], v[56:57], v[68:69], v[76:77] op_sel_hi:[1,0,1] neg_lo:[0,1,0] neg_hi:[0,1,0]
	s_waitcnt lgkmcnt(13)
	v_pk_mul_f32 v[68:69], v[106:107], v[78:79]
	v_pk_mul_f32 v[82:83], v[62:63], v[78:79]
	v_pk_mul_f32 v[70:71], v[182:183], v[118:119] op_sel:[1,0]
	v_pk_fma_f32 v[68:69], v[108:109], v[80:81], v[68:69]
	v_pk_fma_f32 v[82:83], v[64:65], v[80:81], v[82:83]
	v_pk_mul_f32 v[72:73], v[182:183], v[120:121] op_sel:[1,0]
	v_add_f32_e32 v68, v68, v69
	v_add_f32_e32 v82, v82, v83
	v_pk_fma_f32 v[74:75], v[110:111], v[78:79], v[70:71]
	v_add_f32_dpp v68, v68, v68 quad_perm:[1,0,3,2] row_mask:0xf bank_mask:0xf bound_ctrl:1
	v_add_f32_dpp v82, v82, v82 row_ror:8 row_mask:0xf bank_mask:0xf bound_ctrl:1
	v_pk_fma_f32 v[76:77], v[112:113], v[80:81], v[72:73]
	v_add_f32_dpp v68, v68, v68 quad_perm:[2,3,0,1] row_mask:0xf bank_mask:0xf bound_ctrl:1
	ds_read_b128 v[24:27], v84 offset:6656
	ds_read_b128 v[28:31], v84 offset:14848
	v_add_f32_dpp v68, v68, v68 row_half_mirror row_mask:0xf bank_mask:0xf bound_ctrl:1
	ds_read_b128 v[32:35], v84 offset:23040
	ds_read_b128 v[36:39], v84 offset:31232
	v_add_f32_dpp v68, v68, v68 row_ror:8 row_mask:0xf bank_mask:0xf bound_ctrl:1
	ds_read_b128 v[40:43], v84 offset:39424
	v_pk_fma_f32 v[78:79], v[114:115], v[68:69], v[74:75] op_sel_hi:[1,0,1] neg_lo:[0,1,0] neg_hi:[0,1,0]
	v_pk_fma_f32 v[80:81], v[116:117], v[68:69], v[76:77] op_sel_hi:[1,0,1] neg_lo:[0,1,0] neg_hi:[0,1,0]
	s_waitcnt lgkmcnt(11)
	v_pk_mul_f32 v[68:69], v[128:129], v[78:79]
	v_pk_mul_f32 v[88:89], v[122:123], v[78:79]
	v_pk_mul_f32 v[70:71], v[168:169], v[140:141] op_sel_hi:[0,1]
	v_pk_fma_f32 v[68:69], v[130:131], v[80:81], v[68:69]
	v_pk_fma_f32 v[88:89], v[124:125], v[80:81], v[88:89]
	v_pk_mul_f32 v[72:73], v[168:169], v[142:143] op_sel_hi:[0,1]
	v_add_f32_e32 v68, v68, v69
	v_add_f32_e32 v88, v88, v89
	v_pk_fma_f32 v[74:75], v[132:133], v[78:79], v[70:71]
	v_add_f32_dpp v68, v68, v68 quad_perm:[1,0,3,2] row_mask:0xf bank_mask:0xf bound_ctrl:1
	v_add_f32_dpp v88, v88, v88 row_ror:8 row_mask:0xf bank_mask:0xf bound_ctrl:1
	v_pk_fma_f32 v[76:77], v[134:135], v[80:81], v[72:73]
	v_add_f32_dpp v68, v68, v68 quad_perm:[2,3,0,1] row_mask:0xf bank_mask:0xf bound_ctrl:1
	ds_write2st64_b32 v86, v82, v88 offset0:44 offset1:46
	ds_read_b128 v[46:49], v84 offset:6912
	v_add_f32_dpp v68, v68, v68 row_half_mirror row_mask:0xf bank_mask:0xf bound_ctrl:1
	ds_read_b128 v[50:53], v84 offset:15104
	ds_read_b128 v[54:57], v84 offset:23296
	v_add_f32_dpp v68, v68, v68 row_ror:8 row_mask:0xf bank_mask:0xf bound_ctrl:1
	ds_read_b128 v[58:61], v84 offset:31488
	ds_read_b128 v[62:65], v84 offset:39680
	v_pk_fma_f32 v[78:79], v[136:137], v[68:69], v[74:75] op_sel_hi:[1,0,1] neg_lo:[0,1,0] neg_hi:[0,1,0]
	v_pk_fma_f32 v[80:81], v[138:139], v[68:69], v[76:77] op_sel_hi:[1,0,1] neg_lo:[0,1,0] neg_hi:[0,1,0]
	s_waitcnt lgkmcnt(11)
	v_pk_mul_f32 v[68:69], v[2:3], v[78:79]
	v_pk_mul_f32 v[82:83], v[144:145], v[78:79]
	v_pk_mul_f32 v[70:71], v[168:169], v[14:15] op_sel:[1,0]
	v_pk_fma_f32 v[68:69], v[4:5], v[80:81], v[68:69]
	v_pk_fma_f32 v[82:83], v[146:147], v[80:81], v[82:83]
	v_pk_mul_f32 v[72:73], v[168:169], v[16:17] op_sel:[1,0]
	v_add_f32_e32 v68, v68, v69
	v_add_f32_e32 v82, v82, v83
	v_pk_fma_f32 v[74:75], v[6:7], v[78:79], v[70:71]
	v_add_f32_dpp v68, v68, v68 quad_perm:[1,0,3,2] row_mask:0xf bank_mask:0xf bound_ctrl:1
	v_add_f32_dpp v82, v82, v82 row_ror:8 row_mask:0xf bank_mask:0xf bound_ctrl:1
	v_pk_fma_f32 v[76:77], v[8:9], v[80:81], v[72:73]
	v_add_f32_dpp v68, v68, v68 quad_perm:[2,3,0,1] row_mask:0xf bank_mask:0xf bound_ctrl:1
	ds_read_b128 v[106:109], v84 offset:7168
	ds_read_b128 v[110:113], v84 offset:15360
	v_add_f32_dpp v68, v68, v68 row_half_mirror row_mask:0xf bank_mask:0xf bound_ctrl:1
	ds_read_b128 v[114:117], v84 offset:23552
	ds_read_b128 v[118:121], v84 offset:31744
	v_add_f32_dpp v68, v68, v68 row_ror:8 row_mask:0xf bank_mask:0xf bound_ctrl:1
	ds_read_b128 v[122:125], v84 offset:39936
	v_pk_fma_f32 v[78:79], v[10:11], v[68:69], v[74:75] op_sel_hi:[1,0,1] neg_lo:[0,1,0] neg_hi:[0,1,0]
	v_pk_fma_f32 v[80:81], v[12:13], v[68:69], v[76:77] op_sel_hi:[1,0,1] neg_lo:[0,1,0] neg_hi:[0,1,0]
	s_waitcnt lgkmcnt(11)
	v_pk_mul_f32 v[68:69], v[24:25], v[78:79]
	v_pk_mul_f32 v[88:89], v[18:19], v[78:79]
	v_pk_mul_f32 v[70:71], v[170:171], v[36:37] op_sel_hi:[0,1]
	v_pk_fma_f32 v[68:69], v[26:27], v[80:81], v[68:69]
	v_pk_fma_f32 v[88:89], v[20:21], v[80:81], v[88:89]
	v_pk_mul_f32 v[72:73], v[170:171], v[38:39] op_sel_hi:[0,1]
	v_add_f32_e32 v68, v68, v69
	v_add_f32_e32 v88, v88, v89
	v_pk_fma_f32 v[74:75], v[28:29], v[78:79], v[70:71]
	v_add_f32_dpp v68, v68, v68 quad_perm:[1,0,3,2] row_mask:0xf bank_mask:0xf bound_ctrl:1
	v_add_f32_dpp v88, v88, v88 row_ror:8 row_mask:0xf bank_mask:0xf bound_ctrl:1
	v_pk_fma_f32 v[76:77], v[30:31], v[80:81], v[72:73]
	v_add_f32_dpp v68, v68, v68 quad_perm:[2,3,0,1] row_mask:0xf bank_mask:0xf bound_ctrl:1
	ds_write2st64_b32 v86, v82, v88 offset0:48 offset1:50
	ds_read_b128 v[128:131], v84 offset:7424
	v_add_f32_dpp v68, v68, v68 row_half_mirror row_mask:0xf bank_mask:0xf bound_ctrl:1
	ds_read_b128 v[132:135], v84 offset:15616
	ds_read_b128 v[136:139], v84 offset:23808
	v_add_f32_dpp v68, v68, v68 row_ror:8 row_mask:0xf bank_mask:0xf bound_ctrl:1
	ds_read_b128 v[140:143], v84 offset:32000
	ds_read_b128 v[144:147], v84 offset:40192
	v_pk_fma_f32 v[78:79], v[32:33], v[68:69], v[74:75] op_sel_hi:[1,0,1] neg_lo:[0,1,0] neg_hi:[0,1,0]
	v_pk_fma_f32 v[80:81], v[34:35], v[68:69], v[76:77] op_sel_hi:[1,0,1] neg_lo:[0,1,0] neg_hi:[0,1,0]
	s_waitcnt lgkmcnt(11)
	v_pk_mul_f32 v[68:69], v[46:47], v[78:79]
	v_pk_mul_f32 v[82:83], v[40:41], v[78:79]
	v_pk_mul_f32 v[70:71], v[170:171], v[58:59] op_sel:[1,0]
	v_pk_fma_f32 v[68:69], v[48:49], v[80:81], v[68:69]
	v_pk_fma_f32 v[82:83], v[42:43], v[80:81], v[82:83]
	v_pk_mul_f32 v[72:73], v[170:171], v[60:61] op_sel:[1,0]
	v_add_f32_e32 v68, v68, v69
	v_add_f32_e32 v82, v82, v83
	v_pk_fma_f32 v[74:75], v[50:51], v[78:79], v[70:71]
	v_add_f32_dpp v68, v68, v68 quad_perm:[1,0,3,2] row_mask:0xf bank_mask:0xf bound_ctrl:1
	v_add_f32_dpp v82, v82, v82 row_ror:8 row_mask:0xf bank_mask:0xf bound_ctrl:1
	v_pk_fma_f32 v[76:77], v[52:53], v[80:81], v[72:73]
	v_add_f32_dpp v68, v68, v68 quad_perm:[2,3,0,1] row_mask:0xf bank_mask:0xf bound_ctrl:1
	ds_read_b128 v[2:5], v84 offset:7680
	ds_read_b128 v[6:9], v84 offset:15872
	v_add_f32_dpp v68, v68, v68 row_half_mirror row_mask:0xf bank_mask:0xf bound_ctrl:1
	ds_read_b128 v[10:13], v84 offset:24064
	ds_read_b128 v[14:17], v84 offset:32256
	v_add_f32_dpp v68, v68, v68 row_ror:8 row_mask:0xf bank_mask:0xf bound_ctrl:1
	ds_read_b128 v[18:21], v84 offset:40448
	v_pk_fma_f32 v[78:79], v[54:55], v[68:69], v[74:75] op_sel_hi:[1,0,1] neg_lo:[0,1,0] neg_hi:[0,1,0]
	v_pk_fma_f32 v[80:81], v[56:57], v[68:69], v[76:77] op_sel_hi:[1,0,1] neg_lo:[0,1,0] neg_hi:[0,1,0]
	s_waitcnt lgkmcnt(11)
	v_pk_mul_f32 v[68:69], v[106:107], v[78:79]
	v_pk_mul_f32 v[88:89], v[62:63], v[78:79]
	v_pk_mul_f32 v[70:71], v[172:173], v[118:119] op_sel_hi:[0,1]
	v_pk_fma_f32 v[68:69], v[108:109], v[80:81], v[68:69]
	v_pk_fma_f32 v[88:89], v[64:65], v[80:81], v[88:89]
	v_pk_mul_f32 v[72:73], v[172:173], v[120:121] op_sel_hi:[0,1]
	v_add_f32_e32 v68, v68, v69
	v_add_f32_e32 v88, v88, v89
	v_pk_fma_f32 v[74:75], v[110:111], v[78:79], v[70:71]
	v_add_f32_dpp v68, v68, v68 quad_perm:[1,0,3,2] row_mask:0xf bank_mask:0xf bound_ctrl:1
	v_add_f32_dpp v88, v88, v88 row_ror:8 row_mask:0xf bank_mask:0xf bound_ctrl:1
	v_pk_fma_f32 v[76:77], v[112:113], v[80:81], v[72:73]
	v_add_f32_dpp v68, v68, v68 quad_perm:[2,3,0,1] row_mask:0xf bank_mask:0xf bound_ctrl:1
	ds_write2st64_b32 v86, v82, v88 offset0:52 offset1:54
	ds_read_b128 v[24:27], v84 offset:7936
	v_add_f32_dpp v68, v68, v68 row_half_mirror row_mask:0xf bank_mask:0xf bound_ctrl:1
	ds_read_b128 v[28:31], v84 offset:16128
	ds_read_b128 v[32:35], v84 offset:24320
	v_add_f32_dpp v68, v68, v68 row_ror:8 row_mask:0xf bank_mask:0xf bound_ctrl:1
	ds_read_b128 v[36:39], v84 offset:32512
	ds_read_b128 v[40:43], v84 offset:40704
	v_pk_fma_f32 v[78:79], v[114:115], v[68:69], v[74:75] op_sel_hi:[1,0,1] neg_lo:[0,1,0] neg_hi:[0,1,0]
	v_pk_fma_f32 v[80:81], v[116:117], v[68:69], v[76:77] op_sel_hi:[1,0,1] neg_lo:[0,1,0] neg_hi:[0,1,0]
	s_waitcnt lgkmcnt(11)
	v_pk_mul_f32 v[68:69], v[128:129], v[78:79]
	v_pk_mul_f32 v[82:83], v[122:123], v[78:79]
	v_pk_mul_f32 v[70:71], v[172:173], v[140:141] op_sel:[1,0]
	v_pk_fma_f32 v[68:69], v[130:131], v[80:81], v[68:69]
	v_pk_fma_f32 v[82:83], v[124:125], v[80:81], v[82:83]
	v_pk_mul_f32 v[72:73], v[172:173], v[142:143] op_sel:[1,0]
	v_add_f32_e32 v68, v68, v69
	v_add_f32_e32 v82, v82, v83
	v_pk_fma_f32 v[74:75], v[132:133], v[78:79], v[70:71]
	v_add_f32_dpp v68, v68, v68 quad_perm:[1,0,3,2] row_mask:0xf bank_mask:0xf bound_ctrl:1
	v_add_f32_dpp v82, v82, v82 row_ror:8 row_mask:0xf bank_mask:0xf bound_ctrl:1
	v_pk_fma_f32 v[76:77], v[134:135], v[80:81], v[72:73]
	v_add_f32_dpp v68, v68, v68 quad_perm:[2,3,0,1] row_mask:0xf bank_mask:0xf bound_ctrl:1
	s_nop 1
	v_add_f32_dpp v68, v68, v68 row_half_mirror row_mask:0xf bank_mask:0xf bound_ctrl:1
	s_nop 1
	v_add_f32_dpp v68, v68, v68 row_ror:8 row_mask:0xf bank_mask:0xf bound_ctrl:1
	v_pk_fma_f32 v[78:79], v[136:137], v[68:69], v[74:75] op_sel_hi:[1,0,1] neg_lo:[0,1,0] neg_hi:[0,1,0]
	v_pk_fma_f32 v[80:81], v[138:139], v[68:69], v[76:77] op_sel_hi:[1,0,1] neg_lo:[0,1,0] neg_hi:[0,1,0]
	s_waitcnt lgkmcnt(6)
	v_pk_mul_f32 v[68:69], v[2:3], v[78:79]
	v_pk_mul_f32 v[88:89], v[144:145], v[78:79]
	v_pk_mul_f32 v[70:71], v[174:175], v[14:15] op_sel_hi:[0,1]
	v_pk_fma_f32 v[68:69], v[4:5], v[80:81], v[68:69]
	v_pk_fma_f32 v[88:89], v[146:147], v[80:81], v[88:89]
	v_pk_mul_f32 v[72:73], v[174:175], v[16:17] op_sel_hi:[0,1]
	v_add_f32_e32 v68, v68, v69
	v_add_f32_e32 v88, v88, v89
	v_pk_fma_f32 v[74:75], v[6:7], v[78:79], v[70:71]
	v_add_f32_dpp v68, v68, v68 quad_perm:[1,0,3,2] row_mask:0xf bank_mask:0xf bound_ctrl:1
	v_add_f32_dpp v88, v88, v88 row_ror:8 row_mask:0xf bank_mask:0xf bound_ctrl:1
	v_pk_fma_f32 v[76:77], v[8:9], v[80:81], v[72:73]
	v_add_f32_dpp v68, v68, v68 quad_perm:[2,3,0,1] row_mask:0xf bank_mask:0xf bound_ctrl:1
	ds_write2st64_b32 v86, v82, v88 offset0:56 offset1:58
	s_nop 0
	v_add_f32_dpp v68, v68, v68 row_half_mirror row_mask:0xf bank_mask:0xf bound_ctrl:1
	s_nop 1
	v_add_f32_dpp v68, v68, v68 row_ror:8 row_mask:0xf bank_mask:0xf bound_ctrl:1
	v_pk_fma_f32 v[78:79], v[10:11], v[68:69], v[74:75] op_sel_hi:[1,0,1] neg_lo:[0,1,0] neg_hi:[0,1,0]
	v_pk_fma_f32 v[80:81], v[12:13], v[68:69], v[76:77] op_sel_hi:[1,0,1] neg_lo:[0,1,0] neg_hi:[0,1,0]
	s_waitcnt lgkmcnt(1)
	v_pk_mul_f32 v[68:69], v[24:25], v[78:79]
	v_pk_mul_f32 v[82:83], v[18:19], v[78:79]
	v_pk_mul_f32 v[70:71], v[174:175], v[36:37] op_sel:[1,0]
	v_pk_fma_f32 v[68:69], v[26:27], v[80:81], v[68:69]
	v_pk_fma_f32 v[82:83], v[20:21], v[80:81], v[82:83]
	v_pk_mul_f32 v[72:73], v[174:175], v[38:39] op_sel:[1,0]
	v_add_f32_e32 v68, v68, v69
	v_add_f32_e32 v82, v82, v83
	v_pk_fma_f32 v[74:75], v[28:29], v[78:79], v[70:71]
	v_add_f32_dpp v68, v68, v68 quad_perm:[1,0,3,2] row_mask:0xf bank_mask:0xf bound_ctrl:1
	v_add_f32_dpp v82, v82, v82 row_ror:8 row_mask:0xf bank_mask:0xf bound_ctrl:1
	v_pk_fma_f32 v[76:77], v[30:31], v[80:81], v[72:73]
	v_add_f32_dpp v68, v68, v68 quad_perm:[2,3,0,1] row_mask:0xf bank_mask:0xf bound_ctrl:1
	s_nop 1
	v_add_f32_dpp v68, v68, v68 row_half_mirror row_mask:0xf bank_mask:0xf bound_ctrl:1
	s_nop 1
	v_add_f32_dpp v68, v68, v68 row_ror:8 row_mask:0xf bank_mask:0xf bound_ctrl:1
	v_pk_fma_f32 v[78:79], v[32:33], v[68:69], v[74:75] op_sel_hi:[1,0,1] neg_lo:[0,1,0] neg_hi:[0,1,0]
	v_pk_fma_f32 v[80:81], v[34:35], v[68:69], v[76:77] op_sel_hi:[1,0,1] neg_lo:[0,1,0] neg_hi:[0,1,0]
	v_pk_mul_f32 v[88:89], v[40:41], v[78:79]
	v_pk_fma_f32 v[88:89], v[42:43], v[80:81], v[88:89]
	v_add_f32_e32 v88, v88, v89
	s_nop 1
	v_add_f32_dpp v88, v88, v88 row_ror:8 row_mask:0xf bank_mask:0xf bound_ctrl:1
	ds_write2st64_b32 v86, v82, v88 offset0:60 offset1:62
	v_add_u32_e32 v101, 1, v101
